# stick-breaking mixer: next K/V tile global loads issued before the current tile's math (register prefetch)
# speedup vs baseline: 1.0297x; 1.0025x over previous
; #define LAS __attribute__((address_space(3)))
; template <int MODE>
; __device__ __forceinline__ void attn_wave(LAS unsigned char* lds, const bf16_t* qkv, bf16_t* Yout, const float* sinks, int wi) {
;     ...
;     const int qb = (MODE == MODE_A) ? (wi & 127) : (wi & 31), h = (MODE == MODE_A) ? ((wi >> 7) & 1) * 4 : ((wi >> 5) & 7), b = wi >> 8;
;     const int q0 = (MODE == MODE_A) ? qb * 16 : qb * 64;
;     constexpr int QSTEP = (MODE == MODE_A) ? 0 : 16, HSTEP = (MODE == MODE_A) ? 1 : 0;
;     const bf16_t* base = qkv + (size_t)b * SEQ * QP;
;     const bf16_t* qp = base + (MODE == MODE_A ? C_AQ + h * 64 : C_CQ + h * 64);
;     const bf16_t* kp = base + (MODE == MODE_A ? C_AK + (h >> 2) * 64 : C_CK + h * 64);
;     const bf16_t* vp = base + (MODE == MODE_A ? C_AV + (h >> 2) * 64 : C_CV + h * 64);
;     LAS unsigned char* Vs = lds + AW_VT + wid * ATT_TILE;
;     const LAS float* lutp = (const LAS float*)(lds + AW_LUT) + h * 128;
;     bf16x8 qf[NQT][2];
; #pragma unroll
;     for (int qt = 0; qt < NQT; ++qt)
; #pragma unroll
;         for (int ks = 0; ks < 2; ++ks) qf[qt][ks] = *(const bf16x8*)(qp + (size_t)(q0 + qt * QSTEP + c) * QP + qt * HSTEP * 64 + ks * 32 + g * 8);
;     f32x4 o[NQT][4];
; #pragma unroll
;     for (int qt = 0; qt < NQT; ++qt)
; #pragma unroll
;         for (int dt = 0; dt < 4; ++dt) o[qt][dt] = (f32x4){0.f, 0.f, 0.f, 0.f};
;     float mrun[NQT], lrun[NQT], carry[NQT];
; #pragma unroll
;     for (int qt = 0; qt < NQT; ++qt) { mrun[qt] = -1e30f; lrun[qt] = 0.f; carry[qt] = 0.f; }
;     const int kb_hi = (MODE == MODE_A) ? ((q0 + 15) >> 5) : ((q0 + 63) >> 5);
;     int kb_lo = 0;
;     if (MODE == MODE_A) { const int lo = q0 - 127; kb_lo = lo > 0 ? (lo >> 5) : 0; }
;     ...
;         const int k0 = kb * 32;
;         u32x4 vr[4];
; #pragma unroll
;         for (int i = 0; i < 4; ++i) { const int e = lane + 64 * i; vr[i] = *(const u32x4*)(vp + (size_t)(k0 + (e >> 3)) * QP + (e & 7) * 8); }
;         bf16x8 kf[2][2];
; #pragma unroll
;         for (int nt = 0; nt < 2; ++nt)
; #pragma unroll
;             for (int ks = 0; ks < 2; ++ks) kf[nt][ks] = *(const bf16x8*)(kp + (size_t)(k0 + 16 * nt + c) * QP + ks * 32 + g * 8);
.LBB0_335:
	s_and_b64 vcc, exec, s[0:1]
	s_cbranch_vccz .LBB0_347
	s_add_i32 s0, s26, 0xfffffc00
	s_lshl_b32 s1, s0, 6
	s_and_b32 s13, s1, 0x7c0
	s_lshl_b32 s1, s0, 3
	s_and_b32 s19, s1, 0xf800
	s_mul_i32 s1, s19, 0x1c30
	v_readlane_b32 s4, v252, 52
	v_readlane_b32 s5, v252, 53
	s_add_u32 s1, s4, s1
	s_addc_u32 s4, s5, 0
	s_lshl_b32 s0, s0, 1
	v_mov_b32_e32 v152, v214
	s_and_b32 s27, s0, 0x1c0
	s_lshl_b32 s0, s27, 1
	v_and_b32_e32 v153, 15, v152
	s_add_u32 s0, s1, s0
	v_or_b32_e32 v140, s13, v153
	s_addc_u32 s1, s4, 0
	v_and_b32_e32 v2, 48, v152
	v_mov_b32_e32 v3, v0
	v_mul_u32_u24_e32 v1, 0xe18, v140
	v_lshlrev_b32_e32 v8, 1, v1
	v_mov_b32_e32 v9, v0
	v_lshl_add_u64 v[2:3], s[0:1], 0, v[2:3]
	v_lshl_add_u64 v[8:9], v[2:3], 0, v[8:9]
	s_mov_b64 s[4:5], 0x1000
	v_lshl_add_u64 v[10:11], v[8:9], 0, s[4:5]
	s_movk_i32 s4, 0x1000
	v_add_co_u32_e32 v12, vcc, s4, v8
	s_mov_b32 s4, 0x1d000
	s_nop 0
	v_addc_co_u32_e32 v13, vcc, 0, v9, vcc
	global_load_dwordx4 v[40:43], v[12:13], off
	global_load_dwordx4 v[44:47], v[10:11], off offset:64
	v_add_co_u32_e32 v10, vcc, s4, v8
	s_mov_b32 s4, 0x39000
	s_nop 0
	v_addc_co_u32_e32 v11, vcc, 0, v9, vcc
	global_load_dwordx4 v[48:51], v[10:11], off offset:768
	global_load_dwordx4 v[52:55], v[10:11], off offset:832
	v_add_co_u32_e32 v10, vcc, s4, v8
	s_mov_b32 s4, 0x55000
	s_nop 0
	v_addc_co_u32_e32 v11, vcc, 0, v9, vcc
	v_add_co_u32_e32 v8, vcc, s4, v8
	global_load_dwordx4 v[56:59], v[10:11], off offset:1536
	global_load_dwordx4 v[60:63], v[10:11], off offset:1600
	v_addc_co_u32_e32 v9, vcc, 0, v9, vcc
	global_load_dwordx4 v[64:67], v[8:9], off offset:2304
	global_load_dwordx4 v[72:75], v[8:9], off offset:2368
	v_lshlrev_b32_e32 v8, 4, v152
	v_readfirstlane_b32 s4, v152
	v_and_b32_e32 v8, 0x70, v8
	v_mov_b32_e32 v9, v0
	s_lshr_b32 s4, s4, 6
	v_lshl_add_u64 v[10:11], s[0:1], 0, v[8:9]
	s_mov_b64 s[0:1], 0x1800
	v_bfe_u32 v1, v152, 4, 2
	s_mulk_i32 s4, 0x2400
	v_lshl_add_u64 v[142:143], v[10:11], 0, s[0:1]
	s_mov_b64 s[0:1], 0x1400
	s_add_i32 s4, s4, 0
	v_lshl_add_u64 v[144:145], v[2:3], 0, s[0:1]
	v_lshlrev_b32_e32 v154, 2, v1
	v_bfe_u32 v2, v152, 2, 2
	v_or_b32_e32 v2, v154, v2
	v_mov_b32_e32 v3, s4
	v_mad_u32_u24 v9, v2, s84, v3
	v_xor_b32_e32 v2, 1, v1
	v_add_u32_e32 v8, s4, v8
	v_cmp_gt_u32_e64 s[4:5], v2, v1
	v_xor_b32_e32 v2, 2, v1
	v_lshlrev_b32_e32 v12, 3, v152
	v_cmp_gt_u32_e64 s[6:7], v2, v1
	v_xor_b32_e32 v2, 3, v1
	v_bfe_u32 v155, v152, 3, 3
	v_and_b32_e32 v10, 24, v12
	v_cmp_gt_u32_e64 s[8:9], v2, v1
	v_mul_u32_u24_e32 v11, 0x90, v155
	v_mov_b32_e32 v2, v0
	v_mov_b32_e32 v3, v0
	v_or_b32_e32 v146, 16, v140
	v_or_b32_e32 v148, 32, v140
	v_or_b32_e32 v150, 48, v140
	v_mov_b32_e32 v1, v0
	v_add_u32_e32 v156, v8, v11
	v_add_u32_e32 v157, v9, v10
	v_mov_b64_e32 v[90:91], v[2:3]
	v_mov_b64_e32 v[94:95], v[2:3]
	v_mov_b64_e32 v[98:99], v[2:3]
	v_mov_b64_e32 v[102:103], v[2:3]
	v_mov_b64_e32 v[86:87], v[2:3]
	v_mov_b64_e32 v[82:83], v[2:3]
	v_mov_b64_e32 v[78:79], v[2:3]
	v_mov_b64_e32 v[70:71], v[2:3]
	v_mov_b64_e32 v[38:39], v[2:3]
	v_mov_b64_e32 v[34:35], v[2:3]
	v_mov_b64_e32 v[30:31], v[2:3]
	v_mov_b64_e32 v[26:27], v[2:3]
	v_mov_b64_e32 v[22:23], v[2:3]
	v_mov_b64_e32 v[18:19], v[2:3]
	v_mov_b64_e32 v[14:15], v[2:3]
	v_mov_b64_e32 v[10:11], v[2:3]
	v_mov_b64_e32 v[106:107], v[2:3]
	s_or_b32 s36, s13, 15
	s_or_b32 s44, s13, 31
	s_or_b32 s45, s13, 47
	s_or_b32 s46, s13, 63
	v_mov_b32_e32 v141, v150
	v_mov_b32_e32 v147, v148
	v_mov_b32_e32 v149, v146
	v_mov_b32_e32 v151, v140
	s_or_b32 s47, s13, 32
	v_mov_b64_e32 v[88:89], v[0:1]
	v_mov_b64_e32 v[92:93], v[0:1]
	v_mov_b64_e32 v[96:97], v[0:1]
	v_mov_b64_e32 v[100:101], v[0:1]
	v_mov_b64_e32 v[84:85], v[0:1]
	v_mov_b64_e32 v[80:81], v[0:1]
	v_mov_b64_e32 v[76:77], v[0:1]
	v_mov_b64_e32 v[68:69], v[0:1]
	v_mov_b64_e32 v[36:37], v[0:1]
	v_mov_b64_e32 v[32:33], v[0:1]
	v_mov_b64_e32 v[28:29], v[0:1]
	v_mov_b64_e32 v[24:25], v[0:1]
	v_mov_b64_e32 v[20:21], v[0:1]
	v_mov_b64_e32 v[16:17], v[0:1]
	v_mov_b64_e32 v[12:13], v[0:1]
	v_mov_b64_e32 v[8:9], v[0:1]
	v_mov_b64_e32 v[104:105], v[0:1]
	v_add_u32_e32 v1, s47, v155
	v_add_u32_e32 v206, 8, v1
	v_mad_u64_u32 v[2:3], s[0:1], v1, s85, v[142:143]
	v_mad_u64_u32 v[232:233], s[0:1], v206, s85, v[142:143]
	global_load_dwordx4 v[228:231], v[2:3], off
	v_add_u32_e32 v2, 16, v1
	global_load_dwordx4 v[232:235], v[232:233], off
	v_add_u32_e32 v1, 24, v1
	v_mad_u64_u32 v[2:3], s[0:1], v2, s85, v[142:143]
	v_mad_u64_u32 v[240:241], s[0:1], v1, s85, v[142:143]
	global_load_dwordx4 v[236:239], v[2:3], off
	v_add_u32_e32 v1, s47, v153
	global_load_dwordx4 v[240:243], v[240:241], off
	v_mad_u64_u32 v[2:3], s[0:1], v1, s85, v[144:145]
	v_add_u32_e32 v1, 16, v1
	global_load_dwordx4 v[190:193], v[2:3], off
	global_load_dwordx4 v[194:197], v[2:3], off offset:64
	v_mad_u64_u32 v[2:3], s[0:1], v1, s85, v[144:145]
	s_nop 0
	global_load_dwordx4 v[198:201], v[2:3], off
	global_load_dwordx4 v[202:205], v[2:3], off offset:64
	s_branch .LBB0_338

; #define LAS __attribute__((address_space(3)))
; template <int MODE>
; __device__ __forceinline__ void attn_wave(LAS unsigned char* lds, const bf16_t* qkv, bf16_t* Yout, const float* sinks, int wi) {
;     ...
;         const int k0 = kb * 32;
;         u32x4 vr[4];
; #pragma unroll
;         for (int i = 0; i < 4; ++i) { const int e = lane + 64 * i; vr[i] = *(const u32x4*)(vp + (size_t)(k0 + (e >> 3)) * QP + (e & 7) * 8); }
;         bf16x8 kf[2][2];
; #pragma unroll
;         for (int nt = 0; nt < 2; ++nt)
; #pragma unroll
;             for (int ks = 0; ks < 2; ++ks) kf[nt][ks] = *(const bf16x8*)(kp + (size_t)(k0 + 16 * nt + c) * QP + ks * 32 + g * 8);
; #pragma unroll
;         for (int i = 0; i < 4; ++i) { const int e = lane + 64 * i; *(LAS u32x4*)(Vs + (e >> 3) * KPB + (e & 7) * 16) = vr[i]; }
;         bf16x8 vfr[4];
;         { const LAS unsigned char* vb = Vs + (4 * g + (c >> 2)) * KPB + (c & 3) * 8;
; #pragma unroll
;           for (int dt = 0; dt < 4; ++dt) vfr[dt] = vfrag(vb + dt * 32); }
;     ...
;             bool live = (k0 <= q0 + QSTEP * qt + 15);
;             if (MODE == MODE_A) live = live && (q0 + QSTEP * qt - (k0 + 31) < 128);
;             if (MODE == MODE_C) { const bool dq = __all(carry[qt] < -150.1f); live = live && !dq; }
;             if (!live) continue;
;             f32x4 s[2];
; #pragma unroll
;             for (int nt = 0; nt < 2; ++nt) { f32x4 z = (f32x4){0.f, 0.f, 0.f, 0.f}; z = MFMA16(kf[nt][0], qf[qt][0], z); s[nt] = MFMA16(kf[nt][1], qf[qt][1], z); }
;             const int dbase = q0 + QSTEP * qt + c - k0 - 4 * g;
;             if (MODE == MODE_A) {
;                 float mx = -1e30f;
; #pragma unroll
;                 for (int nt = 0; nt < 2; ++nt)
; #pragma unroll
;                     for (int j = 0; j < 4; ++j) { const int dist = dbase - (16 * nt + j); const bool valid = (unsigned)dist < 128u;
;                         const float bias2 = lutp[qt * HSTEP * 128 + (dist & 127)];
;                         const float lg = valid ? (s[nt][j] * C1 + bias2) : -1e30f; s[nt][j] = lg; mx = fmaxf(mx, lg); }
;                 mx = fmaxf(mx, __shfl_xor(mx, 16)); mx = fmaxf(mx, __shfl_xor(mx, 32));
;                 const float mnew = fmaxf(mrun[qt], mx); const float alpha = __builtin_amdgcn_exp2f(mrun[qt] - mnew); mrun[qt] = mnew;
;                 float ps = 0.f;
; #pragma unroll
;                 for (int nt = 0; nt < 2; ++nt)
; #pragma unroll
.LBB0_338:
	s_waitcnt vmcnt(0) lgkmcnt(0)
	ds_write_b128 v156, v[228:231]
	ds_write_b128 v156, v[232:235] offset:1152
	ds_write_b128 v156, v[236:239] offset:2304
	ds_write_b128 v156, v[240:243] offset:3456
	v_mov_b64_e32 v[132:133], v[190:191]
	v_mov_b64_e32 v[134:135], v[192:193]
	v_mov_b64_e32 v[136:137], v[194:195]
	v_mov_b64_e32 v[138:139], v[196:197]
	v_mov_b64_e32 v[128:129], v[198:199]
	v_mov_b64_e32 v[130:131], v[200:201]
	v_mov_b64_e32 v[124:125], v[202:203]
	v_mov_b64_e32 v[126:127], v[204:205]
	s_sub_i32 s32, s47, 32
	s_max_i32 s32, s32, 0
	v_add_u32_e32 v1, s32, v155
	v_add_u32_e32 v206, 8, v1
	v_mad_u64_u32 v[2:3], s[0:1], v1, s85, v[142:143]
	v_mad_u64_u32 v[232:233], s[0:1], v206, s85, v[142:143]
	global_load_dwordx4 v[228:231], v[2:3], off
	v_add_u32_e32 v2, 16, v1
	global_load_dwordx4 v[232:235], v[232:233], off
	v_add_u32_e32 v1, 24, v1
	v_mad_u64_u32 v[2:3], s[0:1], v2, s85, v[142:143]
	v_mad_u64_u32 v[240:241], s[0:1], v1, s85, v[142:143]
	global_load_dwordx4 v[236:239], v[2:3], off
	v_add_u32_e32 v1, s32, v153
	global_load_dwordx4 v[240:243], v[240:241], off
	v_mad_u64_u32 v[2:3], s[0:1], v1, s85, v[144:145]
	v_add_u32_e32 v1, 16, v1
	global_load_dwordx4 v[190:193], v[2:3], off
	global_load_dwordx4 v[194:197], v[2:3], off offset:64
	v_mad_u64_u32 v[2:3], s[0:1], v1, s85, v[144:145]
	s_nop 0
	global_load_dwordx4 v[198:201], v[2:3], off
	global_load_dwordx4 v[202:205], v[2:3], off offset:64
	ds_read_b64_tr_b16 v[112:113], v157
	ds_read_b64_tr_b16 v[108:109], v157 offset:32
	ds_read_b64_tr_b16 v[116:117], v157 offset:64
	ds_read_b64_tr_b16 v[120:121], v157 offset:96
	ds_read_b64_tr_b16 v[114:115], v157 offset:2304
	ds_read_b64_tr_b16 v[110:111], v157 offset:2336
	ds_read_b64_tr_b16 v[118:119], v157 offset:2368
	ds_read_b64_tr_b16 v[122:123], v157 offset:2400
	s_mov_b32 s10, 0xc316199a
	s_cmp_gt_u32 s47, s36
	v_cmp_gt_f32_e32 vcc, s10, v104
	s_cselect_b64 s[0:1], -1, 0
	s_cmp_eq_u64 vcc, exec
	s_cselect_b64 s[10:11], -1, 0
	v_add_u32_e32 v3, s47, v154
	s_or_b64 s[0:1], s[0:1], s[10:11]
	s_and_b64 vcc, exec, s[0:1]
	v_add_u32_e32 v163, 1, v3
	v_add_u32_e32 v162, 3, v3
	v_add_u32_e32 v161, 16, v3
	v_add_u32_e32 v160, 17, v3
	v_add_u32_e32 v158, 18, v3
	v_or_b32_e32 v2, 19, v3
	v_or_b32_e32 v159, 2, v3
	s_cbranch_vccnz .LBB0_340
	v_mfma_f32_16x16x32_bf16 v[164:167], v[132:135], v[40:43], 0
	s_mov_b32 s15, 0x3e38aa3b
	v_cmp_gt_u32_e32 vcc, v140, v163
	v_cmp_gt_u32_e64 s[0:1], v140, v159
	v_mfma_f32_16x16x32_bf16 v[164:167], v[136:139], v[44:47], v[164:167]
	v_cmp_gt_u32_e64 s[10:11], v151, v158
	v_mfma_f32_16x16x32_bf16 v[168:171], v[128:131], v[40:43], 0
	v_mfma_f32_16x16x32_bf16 v[168:171], v[124:127], v[44:47], v[168:171]
	s_nop 2
	v_mul_f32_e32 v172, 0x3e38aa3b, v165
	v_exp_f32_e64 v174, -|v172|
	v_mul_f32_e32 v1, 0x3e38aa3b, v164
	v_exp_f32_e64 v173, -|v1|
	v_max_f32_e32 v172, 0, v172
	v_add_f32_e32 v174, 1.0, v174
	v_log_f32_e32 v174, v174
	v_add_f32_e32 v173, 1.0, v173
	v_log_f32_e32 v173, v173
	v_max_f32_e32 v1, 0, v1
	v_add_f32_e32 v172, v172, v174
	v_fma_f32 v165, v165, s15, -v172
	v_cndmask_b32_e32 v182, v226, v165, vcc
	v_mul_f32_e32 v165, 0x3e38aa3b, v166
	v_add_f32_e32 v1, v1, v173
	v_exp_f32_e64 v173, -|v165|
	v_mul_f32_e32 v175, 0x3e38aa3b, v167
	v_exp_f32_e64 v176, -|v175|
	v_fma_f32 v177, v164, s15, -v1
	v_cndmask_b32_e64 v164, 0, -v172, vcc
	v_max_f32_e32 v172, 0, v165
	v_add_f32_e32 v165, 1.0, v173
	v_log_f32_e32 v174, v165
	v_add_f32_e32 v165, 1.0, v176
	v_max_f32_e32 v173, 0, v175
	v_mul_f32_e32 v175, 0x3e38aa3b, v168
	v_log_f32_e32 v165, v165
	v_exp_f32_e64 v178, -|v175|
	v_cmp_gt_u32_e32 vcc, v140, v162
	v_sub_f32_e32 v1, 0, v1
	v_add_f32_e32 v165, v173, v165
	v_add_f32_e32 v173, 1.0, v178
	v_log_f32_e32 v173, v173
	v_cndmask_b32_e64 v176, 0, -v165, vcc
	v_fma_f32 v165, v167, s15, -v165
	v_cndmask_b32_e32 v183, v226, v165, vcc
	v_max_f32_e32 v165, 0, v175
	v_mul_f32_e32 v167, 0x3e38aa3b, v169
	v_add_f32_e32 v165, v165, v173
	v_exp_f32_e64 v173, -|v167|
	v_fma_f32 v168, v168, s15, -v165
	v_cmp_gt_u32_e32 vcc, v140, v161
	v_max_f32_e32 v167, 0, v167
	v_sub_f32_e32 v165, 0, v165
	v_cndmask_b32_e32 v180, v226, v168, vcc
	v_add_f32_e32 v168, 1.0, v173
	v_log_f32_e32 v168, v168
	v_cndmask_b32_e32 v165, 0, v165, vcc
	v_cmp_gt_u32_e32 vcc, v140, v160
	v_add_f32_e32 v167, v167, v168
	v_mul_f32_e32 v168, 0x3e38aa3b, v170
	v_exp_f32_e64 v173, -|v168|
	v_cndmask_b32_e64 v181, 0, -v167, vcc
	v_fma_f32 v167, v169, s15, -v167
	v_cndmask_b32_e32 v184, v226, v167, vcc
	v_add_f32_e32 v167, 1.0, v173
	v_mul_f32_e32 v169, 0x3e38aa3b, v171
	v_log_f32_e32 v167, v167
	v_exp_f32_e64 v175, -|v169|
	v_max_f32_e32 v168, 0, v168
	v_cmp_lt_i32_e32 vcc, v223, v218
	v_add_f32_e32 v167, v168, v167
	v_add_f32_e32 v168, 1.0, v175
	v_log_f32_e32 v175, v168
	v_cndmask_b32_e32 v168, v217, v223, vcc
	v_cmp_lt_i32_e32 vcc, v224, v218
	v_lshlrev_b32_e32 v178, 2, v168
	v_max_f32_e32 v173, 0, v169
	v_cndmask_b32_e32 v168, v217, v224, vcc
	v_lshlrev_b32_e32 v185, 2, v168
	v_xor_b32_e32 v168, 48, v217
	v_cmp_lt_i32_e32 vcc, v168, v218
	v_add_f32_e32 v165, v181, v165
	v_fma_f32 v170, v170, s15, -v167
	v_cndmask_b32_e32 v168, v217, v168, vcc
	v_lshlrev_b32_e32 v186, 2, v168
	v_pk_add_f32 v[168:169], v[172:173], v[174:175]
	v_cmp_gt_u32_e32 vcc, v140, v3
	v_fma_f32 v166, v166, s15, -v168
	v_cndmask_b32_e64 v188, v226, v166, s[0:1]
	v_cndmask_b32_e32 v187, v226, v177, vcc
	v_cndmask_b32_e64 v167, 0, -v167, s[10:11]
	v_cndmask_b32_e32 v166, 0, v1, vcc
	v_cmp_gt_u32_e32 vcc, v151, v2
	v_pk_add_f32 v[172:173], v[166:167], v[164:165]
	v_cndmask_b32_e64 v174, 0, -v168, s[0:1]
	v_cndmask_b32_e64 v175, 0, -v169, vcc
	v_pk_add_f32 v[172:173], v[174:175], v[172:173]
	ds_bpermute_b32 v177, v178, v173
	v_fma_f32 v1, v171, s15, -v169
	ds_bpermute_b32 v169, v185, v173
	ds_bpermute_b32 v171, v186, v173
	v_cndmask_b32_e32 v165, v226, v1, vcc
	s_waitcnt lgkmcnt(2)
; __device__ __forceinline__ unsigned cvtpk(float lo, float hi) { f32x2 v = {lo, hi}; bf16x2_t b = __builtin_convertvector(v, bf16x2_t); return __builtin_bit_cast(unsigned, b); }
; #define MFMA16(a, b, c) __builtin_amdgcn_mfma_f32_16x16x32_bf16((a), (b), (c), 0, 0, 0)
; template <int MODE>
; __device__ __forceinline__ void attn_wave(LAS unsigned char* lds, const bf16_t* qkv, bf16_t* Yout, const float* sinks, int wi) {
;     ...
;             bool live = (k0 <= q0 + QSTEP * qt + 15);
;             if (MODE == MODE_A) live = live && (q0 + QSTEP * qt - (k0 + 31) < 128);
;             if (MODE == MODE_C) { const bool dq = __all(carry[qt] < -150.1f); live = live && !dq; }
;             if (!live) continue;
;             f32x4 s[2];
; #pragma unroll
;             for (int nt = 0; nt < 2; ++nt) { f32x4 z = (f32x4){0.f, 0.f, 0.f, 0.f}; z = MFMA16(kf[nt][0], qf[qt][0], z); s[nt] = MFMA16(kf[nt][1], qf[qt][1], z); }
;     ...
;                     for (int j = 0; j < 4; ++j) { const bool valid = (dbase - (16 * nt + j)) > 0; const float z = s[nt][j] * C1;
;                         const float e = __builtin_amdgcn_exp2f(-fabsf(z));
;                         const float sp = fmaxf(z, 0.f) + __builtin_amdgcn_logf(1.f + e);
;                         lk[nt][j] = valid ? -sp : 0.f; s[nt][j] = valid ? (z - sp) : -1e30f; c4[nt] += lk[nt][j]; } }
;                 float after = 0.f;
; #pragma unroll
;     ...
;                     const float v1 = __shfl_xor(c4[nt], 16), v2 = __shfl_xor(c4[nt], 32), v3 = __shfl_xor(c4[nt], 48);
;                     const float G = (((g ^ 1) > g) ? v1 : 0.f) + (((g ^ 2) > g) ? v2 : 0.f) + (((g ^ 3) > g) ? v3 : 0.f);
;                     const float T = c4[nt] + v1 + v2 + v3;
;                     float sfx = carry[qt] + after + G;
; #pragma unroll
;                     for (int j = 3; j >= 0; --j) { const float w = __builtin_amdgcn_exp2f(s[nt][j] + sfx); s[nt][j] = w; sfx += lk[nt][j]; }
;                     after += T;
;                 }
;                 carry[qt] += after;
;             }
;             u32x4 w; w.x = cvtpk(s[0][0], s[0][1]); w.y = cvtpk(s[0][2], s[0][3]); w.z = cvtpk(s[1][0], s[1][1]); w.w = cvtpk(s[1][2], s[1][3]);
;             const bf16x8 pb = __builtin_bit_cast(bf16x8, w);
; #pragma unroll
;             for (int dt = 0; dt < 4; ++dt) o[qt][dt] = MFMA16(vfr[dt], pb, o[qt][dt]);
	v_cndmask_b32_e64 v1, 0, v177, s[4:5]
	v_pk_add_f32 v[172:173], v[176:177], v[172:173]
	s_waitcnt lgkmcnt(1)
	v_cndmask_b32_e64 v166, 0, v169, s[6:7]
	ds_bpermute_b32 v168, v178, v172
	v_add_f32_e32 v179, v1, v166
	s_waitcnt lgkmcnt(1)
	v_cndmask_b32_e64 v1, 0, v171, s[8:9]
	v_mov_b32_e32 v178, v104
	v_pk_add_f32 v[178:179], v[178:179], v[0:1]
	v_cndmask_b32_e64 v189, v226, v170, s[10:11]
	v_add_f32_e32 v1, v178, v179
	v_add_f32_e32 v165, v1, v165
	v_add_f32_e32 v1, v1, v175
	ds_bpermute_b32 v170, v185, v172
	v_exp_f32_e32 v177, v165
	v_add_f32_e32 v165, v1, v189
	v_add_f32_e32 v1, v167, v1
	v_add_f32_e32 v166, v184, v1
	v_exp_f32_e32 v175, v166
	ds_bpermute_b32 v166, v186, v172
	s_waitcnt lgkmcnt(2)
	v_cndmask_b32_e64 v167, 0, v168, s[4:5]
	s_waitcnt lgkmcnt(1)
	v_cndmask_b32_e64 v178, 0, v170, s[6:7]
	v_pk_add_f32 v[168:169], v[172:173], v[168:169]
	v_add_f32_e32 v178, v167, v178
	v_pk_add_f32 v[168:169], v[168:169], v[170:171]
	v_mov_b32_e32 v167, v0
	v_add_f32_e32 v1, v181, v1
	s_waitcnt lgkmcnt(0)
	v_pk_add_f32 v[168:169], v[168:169], v[166:167]
	v_add_f32_e32 v1, v180, v1
	v_cndmask_b32_e64 v180, 0, v166, s[8:9]
	v_mov_b32_e32 v179, v104
	v_mov_b32_e32 v181, v169
	v_pk_add_f32 v[166:167], v[178:179], v[180:181]
	v_exp_f32_e32 v1, v1
	v_add_f32_e32 v166, v166, v167
	v_add_f32_e32 v167, v183, v166
	v_add_f32_e32 v166, v176, v166
	v_add_f32_e32 v170, v188, v166
	v_add_f32_e32 v166, v174, v166
	v_add_f32_e32 v164, v164, v166
	v_add_f32_e32 v171, v182, v166
	v_add_f32_e32 v164, v187, v164
	v_exp_f32_e32 v167, v167
	v_exp_f32_e32 v171, v171
	v_exp_f32_e32 v164, v164
	v_exp_f32_e32 v166, v170
	v_exp_f32_e32 v170, v165
	v_cvt_pk_bf16_f32 v164, v164, v171
	v_cvt_pk_bf16_f32 v165, v166, v167
	v_cvt_pk_bf16_f32 v166, v1, v175
	v_cvt_pk_bf16_f32 v167, v170, v177
	v_add_f32_e32 v1, v168, v169
	v_add_f32_e32 v104, v104, v1
	v_mfma_f32_16x16x32_bf16 v[100:103], v[112:115], v[164:167], v[100:103]
	v_mfma_f32_16x16x32_bf16 v[96:99], v[108:111], v[164:167], v[96:99]
	v_mfma_f32_16x16x32_bf16 v[92:95], v[116:119], v[164:167], v[92:95]
	v_mfma_f32_16x16x32_bf16 v[88:91], v[120:123], v[164:167], v[88:91]
.LBB0_340:
	s_mov_b32 s10, 0xc316199a
	s_cmp_gt_u32 s47, s44
	v_cmp_gt_f32_e32 vcc, s10, v105
	s_cselect_b64 s[0:1], -1, 0
	s_cmp_eq_u64 vcc, exec
	s_cselect_b64 s[10:11], -1, 0
	s_or_b64 s[0:1], s[0:1], s[10:11]
	s_and_b64 vcc, exec, s[0:1]
	s_cbranch_vccnz .LBB0_342
	v_mfma_f32_16x16x32_bf16 v[164:167], v[132:135], v[48:51], 0
	s_mov_b32 s15, 0x3e38aa3b
	v_cmp_gt_u32_e32 vcc, v146, v163
	v_cmp_gt_u32_e64 s[0:1], v146, v159
	v_mfma_f32_16x16x32_bf16 v[164:167], v[136:139], v[52:55], v[164:167]
	v_cmp_gt_u32_e64 s[10:11], v149, v158
	v_mfma_f32_16x16x32_bf16 v[168:171], v[128:131], v[48:51], 0
	v_mfma_f32_16x16x32_bf16 v[168:171], v[124:127], v[52:55], v[168:171]
	s_nop 2
	v_mul_f32_e32 v172, 0x3e38aa3b, v165
	v_exp_f32_e64 v174, -|v172|
	v_mul_f32_e32 v1, 0x3e38aa3b, v164
	v_exp_f32_e64 v173, -|v1|
	v_max_f32_e32 v172, 0, v172
	v_add_f32_e32 v174, 1.0, v174
	v_log_f32_e32 v174, v174
	v_add_f32_e32 v173, 1.0, v173
	v_log_f32_e32 v173, v173
	v_max_f32_e32 v1, 0, v1
	v_add_f32_e32 v172, v172, v174
	v_fma_f32 v165, v165, s15, -v172
	v_cndmask_b32_e32 v182, v226, v165, vcc
	v_mul_f32_e32 v165, 0x3e38aa3b, v166
	v_add_f32_e32 v1, v1, v173
	v_exp_f32_e64 v173, -|v165|
	v_mul_f32_e32 v175, 0x3e38aa3b, v167
	v_exp_f32_e64 v176, -|v175|
	v_fma_f32 v177, v164, s15, -v1
	v_cndmask_b32_e64 v164, 0, -v172, vcc
	v_max_f32_e32 v172, 0, v165
	v_add_f32_e32 v165, 1.0, v173
	v_log_f32_e32 v174, v165
	v_add_f32_e32 v165, 1.0, v176
	v_max_f32_e32 v173, 0, v175
	v_mul_f32_e32 v175, 0x3e38aa3b, v168
	v_log_f32_e32 v165, v165
	v_exp_f32_e64 v178, -|v175|
	v_cmp_gt_u32_e32 vcc, v146, v162
	v_sub_f32_e32 v1, 0, v1
	v_add_f32_e32 v165, v173, v165
	v_add_f32_e32 v173, 1.0, v178
	v_log_f32_e32 v173, v173
	v_cndmask_b32_e64 v176, 0, -v165, vcc
	v_fma_f32 v165, v167, s15, -v165
	v_cndmask_b32_e32 v183, v226, v165, vcc
	v_max_f32_e32 v165, 0, v175
	v_mul_f32_e32 v167, 0x3e38aa3b, v169
	v_add_f32_e32 v165, v165, v173
	v_exp_f32_e64 v173, -|v167|
	v_fma_f32 v168, v168, s15, -v165
	v_cmp_gt_u32_e32 vcc, v140, v3
	v_max_f32_e32 v167, 0, v167
	v_sub_f32_e32 v165, 0, v165
	v_cndmask_b32_e32 v180, v226, v168, vcc
	v_add_f32_e32 v168, 1.0, v173
	v_log_f32_e32 v168, v168
	v_cndmask_b32_e32 v165, 0, v165, vcc
	v_cmp_gt_u32_e32 vcc, v146, v160
	v_add_f32_e32 v167, v167, v168
	v_mul_f32_e32 v168, 0x3e38aa3b, v170
	v_exp_f32_e64 v173, -|v168|
	v_cndmask_b32_e64 v181, 0, -v167, vcc
	v_fma_f32 v167, v169, s15, -v167
	v_cndmask_b32_e32 v184, v226, v167, vcc
	v_add_f32_e32 v167, 1.0, v173
	v_mul_f32_e32 v169, 0x3e38aa3b, v171
	v_log_f32_e32 v167, v167
	v_exp_f32_e64 v175, -|v169|
	v_max_f32_e32 v168, 0, v168
	v_cmp_lt_i32_e32 vcc, v223, v218
	v_add_f32_e32 v167, v168, v167
	v_add_f32_e32 v168, 1.0, v175
	v_log_f32_e32 v175, v168
	v_cndmask_b32_e32 v168, v217, v223, vcc
	v_cmp_lt_i32_e32 vcc, v224, v218
	v_lshlrev_b32_e32 v178, 2, v168
	v_max_f32_e32 v173, 0, v169
	v_cndmask_b32_e32 v168, v217, v224, vcc
	v_lshlrev_b32_e32 v185, 2, v168
	v_xor_b32_e32 v168, 48, v217
	v_cmp_lt_i32_e32 vcc, v168, v218
	v_add_f32_e32 v165, v181, v165
	v_fma_f32 v170, v170, s15, -v167
	v_cndmask_b32_e32 v168, v217, v168, vcc
	v_lshlrev_b32_e32 v186, 2, v168
	v_pk_add_f32 v[168:169], v[172:173], v[174:175]
	v_cmp_gt_u32_e32 vcc, v146, v3
	v_fma_f32 v166, v166, s15, -v168
	v_cndmask_b32_e64 v188, v226, v166, s[0:1]
	v_cndmask_b32_e32 v187, v226, v177, vcc
	v_cndmask_b32_e64 v167, 0, -v167, s[10:11]
	v_cndmask_b32_e32 v166, 0, v1, vcc
	v_cmp_gt_u32_e32 vcc, v149, v2
	v_pk_add_f32 v[172:173], v[166:167], v[164:165]
	v_cndmask_b32_e64 v174, 0, -v168, s[0:1]
	v_cndmask_b32_e64 v175, 0, -v169, vcc
	v_pk_add_f32 v[172:173], v[174:175], v[172:173]
	ds_bpermute_b32 v177, v178, v173
	v_fma_f32 v1, v171, s15, -v169
	ds_bpermute_b32 v169, v185, v173
	ds_bpermute_b32 v171, v186, v173
	v_cndmask_b32_e32 v165, v226, v1, vcc
	s_waitcnt lgkmcnt(2)
; __device__ __forceinline__ unsigned cvtpk(float lo, float hi) { f32x2 v = {lo, hi}; bf16x2_t b = __builtin_convertvector(v, bf16x2_t); return __builtin_bit_cast(unsigned, b); }
; #define MFMA16(a, b, c) __builtin_amdgcn_mfma_f32_16x16x32_bf16((a), (b), (c), 0, 0, 0)
; template <int MODE>
; __device__ __forceinline__ void attn_wave(LAS unsigned char* lds, const bf16_t* qkv, bf16_t* Yout, const float* sinks, int wi) {
;     ...
;             bool live = (k0 <= q0 + QSTEP * qt + 15);
;             if (MODE == MODE_A) live = live && (q0 + QSTEP * qt - (k0 + 31) < 128);
;             if (MODE == MODE_C) { const bool dq = __all(carry[qt] < -150.1f); live = live && !dq; }
;             if (!live) continue;
;             f32x4 s[2];
; #pragma unroll
;             for (int nt = 0; nt < 2; ++nt) { f32x4 z = (f32x4){0.f, 0.f, 0.f, 0.f}; z = MFMA16(kf[nt][0], qf[qt][0], z); s[nt] = MFMA16(kf[nt][1], qf[qt][1], z); }
;     ...
;                     for (int j = 0; j < 4; ++j) { const bool valid = (dbase - (16 * nt + j)) > 0; const float z = s[nt][j] * C1;
;                         const float e = __builtin_amdgcn_exp2f(-fabsf(z));
;                         const float sp = fmaxf(z, 0.f) + __builtin_amdgcn_logf(1.f + e);
;                         lk[nt][j] = valid ? -sp : 0.f; s[nt][j] = valid ? (z - sp) : -1e30f; c4[nt] += lk[nt][j]; } }
;                 float after = 0.f;
; #pragma unroll
;     ...
;                     const float v1 = __shfl_xor(c4[nt], 16), v2 = __shfl_xor(c4[nt], 32), v3 = __shfl_xor(c4[nt], 48);
;                     const float G = (((g ^ 1) > g) ? v1 : 0.f) + (((g ^ 2) > g) ? v2 : 0.f) + (((g ^ 3) > g) ? v3 : 0.f);
;                     const float T = c4[nt] + v1 + v2 + v3;
;                     float sfx = carry[qt] + after + G;
; #pragma unroll
;                     for (int j = 3; j >= 0; --j) { const float w = __builtin_amdgcn_exp2f(s[nt][j] + sfx); s[nt][j] = w; sfx += lk[nt][j]; }
;                     after += T;
;                 }
;                 carry[qt] += after;
;             }
;             u32x4 w; w.x = cvtpk(s[0][0], s[0][1]); w.y = cvtpk(s[0][2], s[0][3]); w.z = cvtpk(s[1][0], s[1][1]); w.w = cvtpk(s[1][2], s[1][3]);
;             const bf16x8 pb = __builtin_bit_cast(bf16x8, w);
; #pragma unroll
;             for (int dt = 0; dt < 4; ++dt) o[qt][dt] = MFMA16(vfr[dt], pb, o[qt][dt]);
	v_cndmask_b32_e64 v1, 0, v177, s[4:5]
	v_pk_add_f32 v[172:173], v[176:177], v[172:173]
	s_waitcnt lgkmcnt(1)
	v_cndmask_b32_e64 v166, 0, v169, s[6:7]
	ds_bpermute_b32 v168, v178, v172
	v_add_f32_e32 v179, v1, v166
	s_waitcnt lgkmcnt(1)
	v_cndmask_b32_e64 v1, 0, v171, s[8:9]
	v_mov_b32_e32 v178, v105
	v_pk_add_f32 v[178:179], v[178:179], v[0:1]
	v_cndmask_b32_e64 v189, v226, v170, s[10:11]
	v_add_f32_e32 v1, v178, v179
	v_add_f32_e32 v165, v1, v165
	v_add_f32_e32 v1, v1, v175
	ds_bpermute_b32 v170, v185, v172
	v_exp_f32_e32 v177, v165
	v_add_f32_e32 v165, v1, v189
	v_add_f32_e32 v1, v167, v1
	v_add_f32_e32 v166, v184, v1
	v_exp_f32_e32 v175, v166
	ds_bpermute_b32 v166, v186, v172
	s_waitcnt lgkmcnt(2)
	v_cndmask_b32_e64 v167, 0, v168, s[4:5]
	s_waitcnt lgkmcnt(1)
	v_cndmask_b32_e64 v178, 0, v170, s[6:7]
	v_pk_add_f32 v[168:169], v[172:173], v[168:169]
	v_add_f32_e32 v178, v167, v178
	v_pk_add_f32 v[168:169], v[168:169], v[170:171]
	v_mov_b32_e32 v167, v0
	v_add_f32_e32 v1, v181, v1
	s_waitcnt lgkmcnt(0)
	v_pk_add_f32 v[168:169], v[168:169], v[166:167]
	v_add_f32_e32 v1, v180, v1
	v_cndmask_b32_e64 v180, 0, v166, s[8:9]
	v_mov_b32_e32 v179, v105
	v_mov_b32_e32 v181, v169
	v_pk_add_f32 v[166:167], v[178:179], v[180:181]
	v_exp_f32_e32 v1, v1
	v_add_f32_e32 v166, v166, v167
	v_add_f32_e32 v167, v183, v166
	v_add_f32_e32 v166, v176, v166
	v_add_f32_e32 v170, v188, v166
	v_add_f32_e32 v166, v174, v166
	v_add_f32_e32 v164, v164, v166
	v_add_f32_e32 v171, v182, v166
	v_add_f32_e32 v164, v187, v164
	v_exp_f32_e32 v167, v167
	v_exp_f32_e32 v171, v171
	v_exp_f32_e32 v164, v164
	v_exp_f32_e32 v166, v170
	v_exp_f32_e32 v170, v165
	v_cvt_pk_bf16_f32 v164, v164, v171
	v_cvt_pk_bf16_f32 v165, v166, v167
	v_cvt_pk_bf16_f32 v166, v1, v175
	v_cvt_pk_bf16_f32 v167, v170, v177
	v_add_f32_e32 v1, v168, v169
	v_add_f32_e32 v105, v105, v1
	v_mfma_f32_16x16x32_bf16 v[84:87], v[112:115], v[164:167], v[84:87]
	v_mfma_f32_16x16x32_bf16 v[80:83], v[108:111], v[164:167], v[80:83]
	v_mfma_f32_16x16x32_bf16 v[76:79], v[116:119], v[164:167], v[76:79]
	v_mfma_f32_16x16x32_bf16 v[68:71], v[120:123], v[164:167], v[68:71]
.LBB0_342:
	s_mov_b32 s10, 0xc316199a
	s_cmp_gt_u32 s47, s45
	v_cmp_gt_f32_e32 vcc, s10, v106
	s_cselect_b64 s[0:1], -1, 0
	s_cmp_eq_u64 vcc, exec
	s_cselect_b64 s[10:11], -1, 0
	s_or_b64 s[0:1], s[0:1], s[10:11]
	s_and_b64 vcc, exec, s[0:1]
	s_cbranch_vccnz .LBB0_344
	v_mfma_f32_16x16x32_bf16 v[164:167], v[132:135], v[56:59], 0
	s_mov_b32 s15, 0x3e38aa3b
	v_cmp_gt_u32_e32 vcc, v148, v163
	v_cmp_gt_u32_e64 s[0:1], v148, v159
	v_mfma_f32_16x16x32_bf16 v[164:167], v[136:139], v[60:63], v[164:167]
	v_cmp_gt_u32_e64 s[10:11], v147, v158
	v_mfma_f32_16x16x32_bf16 v[168:171], v[128:131], v[56:59], 0
	v_mfma_f32_16x16x32_bf16 v[168:171], v[124:127], v[60:63], v[168:171]
	s_nop 2
	v_mul_f32_e32 v172, 0x3e38aa3b, v165
	v_exp_f32_e64 v174, -|v172|
	v_mul_f32_e32 v1, 0x3e38aa3b, v164
	v_exp_f32_e64 v173, -|v1|
	v_max_f32_e32 v172, 0, v172
	v_add_f32_e32 v174, 1.0, v174
	v_log_f32_e32 v174, v174
	v_add_f32_e32 v173, 1.0, v173
	v_log_f32_e32 v173, v173
	v_max_f32_e32 v1, 0, v1
	v_add_f32_e32 v172, v172, v174
	v_fma_f32 v165, v165, s15, -v172
	v_cndmask_b32_e32 v182, v226, v165, vcc
	v_mul_f32_e32 v165, 0x3e38aa3b, v166
	v_add_f32_e32 v1, v1, v173
	v_exp_f32_e64 v173, -|v165|
	v_mul_f32_e32 v175, 0x3e38aa3b, v167
	v_exp_f32_e64 v176, -|v175|
	v_fma_f32 v177, v164, s15, -v1
	v_cndmask_b32_e64 v164, 0, -v172, vcc
	v_max_f32_e32 v172, 0, v165
	v_add_f32_e32 v165, 1.0, v173
	v_log_f32_e32 v174, v165
	v_add_f32_e32 v165, 1.0, v176
	v_max_f32_e32 v173, 0, v175
	v_mul_f32_e32 v175, 0x3e38aa3b, v168
	v_log_f32_e32 v165, v165
	v_exp_f32_e64 v178, -|v175|
	v_cmp_gt_u32_e32 vcc, v148, v162
	v_sub_f32_e32 v1, 0, v1
	v_add_f32_e32 v165, v173, v165
	v_add_f32_e32 v173, 1.0, v178
	v_log_f32_e32 v173, v173
	v_cndmask_b32_e64 v176, 0, -v165, vcc
	v_fma_f32 v165, v167, s15, -v165
	v_cndmask_b32_e32 v183, v226, v165, vcc
	v_max_f32_e32 v165, 0, v175
	v_mul_f32_e32 v167, 0x3e38aa3b, v169
	v_add_f32_e32 v165, v165, v173
	v_exp_f32_e64 v173, -|v167|
	v_fma_f32 v168, v168, s15, -v165
	v_cmp_gt_u32_e32 vcc, v148, v161
	v_max_f32_e32 v167, 0, v167
	v_sub_f32_e32 v165, 0, v165
	v_cndmask_b32_e32 v180, v226, v168, vcc
	v_add_f32_e32 v168, 1.0, v173
	v_log_f32_e32 v168, v168
	v_cndmask_b32_e32 v165, 0, v165, vcc
	v_cmp_gt_u32_e32 vcc, v148, v160
	v_add_f32_e32 v167, v167, v168
	v_mul_f32_e32 v168, 0x3e38aa3b, v170
	v_exp_f32_e64 v173, -|v168|
	v_cndmask_b32_e64 v181, 0, -v167, vcc
	v_fma_f32 v167, v169, s15, -v167
	v_cndmask_b32_e32 v184, v226, v167, vcc
	v_add_f32_e32 v167, 1.0, v173
	v_mul_f32_e32 v169, 0x3e38aa3b, v171
	v_log_f32_e32 v167, v167
	v_exp_f32_e64 v175, -|v169|
	v_max_f32_e32 v168, 0, v168
	v_cmp_lt_i32_e32 vcc, v223, v218
	v_add_f32_e32 v167, v168, v167
	v_add_f32_e32 v168, 1.0, v175
	v_log_f32_e32 v175, v168
	v_cndmask_b32_e32 v168, v217, v223, vcc
	v_cmp_lt_i32_e32 vcc, v224, v218
	v_lshlrev_b32_e32 v178, 2, v168
	v_max_f32_e32 v173, 0, v169
	v_cndmask_b32_e32 v168, v217, v224, vcc
	v_lshlrev_b32_e32 v185, 2, v168
	v_xor_b32_e32 v168, 48, v217
	v_cmp_lt_i32_e32 vcc, v168, v218
	v_add_f32_e32 v165, v181, v165
	v_fma_f32 v170, v170, s15, -v167
	v_cndmask_b32_e32 v168, v217, v168, vcc
	v_lshlrev_b32_e32 v186, 2, v168
	v_pk_add_f32 v[168:169], v[172:173], v[174:175]
	v_cmp_gt_u32_e32 vcc, v148, v3
	v_fma_f32 v166, v166, s15, -v168
	v_cndmask_b32_e64 v188, v226, v166, s[0:1]
	v_cndmask_b32_e32 v187, v226, v177, vcc
	v_cndmask_b32_e64 v167, 0, -v167, s[10:11]
	v_cndmask_b32_e32 v166, 0, v1, vcc
	v_cmp_gt_u32_e32 vcc, v147, v2
	v_pk_add_f32 v[172:173], v[166:167], v[164:165]
	v_cndmask_b32_e64 v174, 0, -v168, s[0:1]
	v_cndmask_b32_e64 v175, 0, -v169, vcc
	v_pk_add_f32 v[172:173], v[174:175], v[172:173]
	ds_bpermute_b32 v177, v178, v173
	v_fma_f32 v1, v171, s15, -v169
	ds_bpermute_b32 v169, v185, v173
	ds_bpermute_b32 v171, v186, v173
	v_cndmask_b32_e32 v165, v226, v1, vcc
	s_waitcnt lgkmcnt(2)
; __device__ __forceinline__ unsigned cvtpk(float lo, float hi) { f32x2 v = {lo, hi}; bf16x2_t b = __builtin_convertvector(v, bf16x2_t); return __builtin_bit_cast(unsigned, b); }
; #define MFMA16(a, b, c) __builtin_amdgcn_mfma_f32_16x16x32_bf16((a), (b), (c), 0, 0, 0)
; template <int MODE>
; __device__ __forceinline__ void attn_wave(LAS unsigned char* lds, const bf16_t* qkv, bf16_t* Yout, const float* sinks, int wi) {
;     ...
;                     for (int j = 0; j < 4; ++j) { const bool valid = (dbase - (16 * nt + j)) > 0; const float z = s[nt][j] * C1;
;                         const float e = __builtin_amdgcn_exp2f(-fabsf(z));
;                         const float sp = fmaxf(z, 0.f) + __builtin_amdgcn_logf(1.f + e);
;                         lk[nt][j] = valid ? -sp : 0.f; s[nt][j] = valid ? (z - sp) : -1e30f; c4[nt] += lk[nt][j]; } }
;                 float after = 0.f;
; #pragma unroll
;     ...
;                     const float v1 = __shfl_xor(c4[nt], 16), v2 = __shfl_xor(c4[nt], 32), v3 = __shfl_xor(c4[nt], 48);
;                     const float G = (((g ^ 1) > g) ? v1 : 0.f) + (((g ^ 2) > g) ? v2 : 0.f) + (((g ^ 3) > g) ? v3 : 0.f);
;                     const float T = c4[nt] + v1 + v2 + v3;
;                     float sfx = carry[qt] + after + G;
; #pragma unroll
;                     for (int j = 3; j >= 0; --j) { const float w = __builtin_amdgcn_exp2f(s[nt][j] + sfx); s[nt][j] = w; sfx += lk[nt][j]; }
;                     after += T;
;                 }
;                 carry[qt] += after;
;             }
;             u32x4 w; w.x = cvtpk(s[0][0], s[0][1]); w.y = cvtpk(s[0][2], s[0][3]); w.z = cvtpk(s[1][0], s[1][1]); w.w = cvtpk(s[1][2], s[1][3]);
;             const bf16x8 pb = __builtin_bit_cast(bf16x8, w);
; #pragma unroll
;             for (int dt = 0; dt < 4; ++dt) o[qt][dt] = MFMA16(vfr[dt], pb, o[qt][dt]);
	v_cndmask_b32_e64 v1, 0, v177, s[4:5]
	v_pk_add_f32 v[172:173], v[176:177], v[172:173]
	s_waitcnt lgkmcnt(1)
	v_cndmask_b32_e64 v166, 0, v169, s[6:7]
	ds_bpermute_b32 v168, v178, v172
	v_add_f32_e32 v179, v1, v166
	s_waitcnt lgkmcnt(1)
	v_cndmask_b32_e64 v1, 0, v171, s[8:9]
	v_mov_b32_e32 v178, v106
	v_pk_add_f32 v[178:179], v[178:179], v[0:1]
	v_cndmask_b32_e64 v189, v226, v170, s[10:11]
	v_add_f32_e32 v1, v178, v179
	v_add_f32_e32 v165, v1, v165
	v_add_f32_e32 v1, v1, v175
	ds_bpermute_b32 v170, v185, v172
	v_exp_f32_e32 v177, v165
	v_add_f32_e32 v165, v1, v189
	v_add_f32_e32 v1, v167, v1
	v_add_f32_e32 v166, v184, v1
	v_exp_f32_e32 v175, v166
	ds_bpermute_b32 v166, v186, v172
	s_waitcnt lgkmcnt(2)
	v_cndmask_b32_e64 v167, 0, v168, s[4:5]
	s_waitcnt lgkmcnt(1)
	v_cndmask_b32_e64 v178, 0, v170, s[6:7]
	v_pk_add_f32 v[168:169], v[172:173], v[168:169]
	v_add_f32_e32 v178, v167, v178
	v_pk_add_f32 v[168:169], v[168:169], v[170:171]
	v_mov_b32_e32 v167, v0
	v_add_f32_e32 v1, v181, v1
	s_waitcnt lgkmcnt(0)
	v_pk_add_f32 v[168:169], v[168:169], v[166:167]
	v_add_f32_e32 v1, v180, v1
	v_cndmask_b32_e64 v180, 0, v166, s[8:9]
	v_mov_b32_e32 v179, v106
	v_mov_b32_e32 v181, v169
	v_pk_add_f32 v[166:167], v[178:179], v[180:181]
	v_exp_f32_e32 v1, v1
	v_add_f32_e32 v166, v166, v167
	v_add_f32_e32 v167, v183, v166
	v_add_f32_e32 v166, v176, v166
	v_add_f32_e32 v170, v188, v166
	v_add_f32_e32 v166, v174, v166
	v_add_f32_e32 v164, v164, v166
	v_add_f32_e32 v171, v182, v166
	v_add_f32_e32 v164, v187, v164
	v_exp_f32_e32 v167, v167
	v_exp_f32_e32 v171, v171
	v_exp_f32_e32 v164, v164
	v_exp_f32_e32 v166, v170
	v_exp_f32_e32 v170, v165
	v_cvt_pk_bf16_f32 v164, v164, v171
	v_cvt_pk_bf16_f32 v165, v166, v167
	v_cvt_pk_bf16_f32 v166, v1, v175
	v_cvt_pk_bf16_f32 v167, v170, v177
	v_add_f32_e32 v1, v168, v169
	v_add_f32_e32 v106, v106, v1
	v_mfma_f32_16x16x32_bf16 v[36:39], v[112:115], v[164:167], v[36:39]
	v_mfma_f32_16x16x32_bf16 v[32:35], v[108:111], v[164:167], v[32:35]
	v_mfma_f32_16x16x32_bf16 v[28:31], v[116:119], v[164:167], v[28:31]
	v_mfma_f32_16x16x32_bf16 v[24:27], v[120:123], v[164:167], v[24:27]
; #define MFMA16(a, b, c) __builtin_amdgcn_mfma_f32_16x16x32_bf16((a), (b), (c), 0, 0, 0)
; template <int MODE>
; __device__ __forceinline__ void attn_wave(LAS unsigned char* lds, const bf16_t* qkv, bf16_t* Yout, const float* sinks, int wi) {
;     ...
;             bool live = (k0 <= q0 + QSTEP * qt + 15);
;             if (MODE == MODE_A) live = live && (q0 + QSTEP * qt - (k0 + 31) < 128);
;             if (MODE == MODE_C) { const bool dq = __all(carry[qt] < -150.1f); live = live && !dq; }
;             if (!live) continue;
;             f32x4 s[2];
; #pragma unroll
;             for (int nt = 0; nt < 2; ++nt) { f32x4 z = (f32x4){0.f, 0.f, 0.f, 0.f}; z = MFMA16(kf[nt][0], qf[qt][0], z); s[nt] = MFMA16(kf[nt][1], qf[qt][1], z); }
;             const int dbase = q0 + QSTEP * qt + c - k0 - 4 * g;
;             if (MODE == MODE_A) {
;                 float mx = -1e30f;
; #pragma unroll
;                 for (int nt = 0; nt < 2; ++nt)
; #pragma unroll
;                     for (int j = 0; j < 4; ++j) { const int dist = dbase - (16 * nt + j); const bool valid = (unsigned)dist < 128u;
;                         const float bias2 = lutp[qt * HSTEP * 128 + (dist & 127)];
;                         const float lg = valid ? (s[nt][j] * C1 + bias2) : -1e30f; s[nt][j] = lg; mx = fmaxf(mx, lg); }
;                 mx = fmaxf(mx, __shfl_xor(mx, 16)); mx = fmaxf(mx, __shfl_xor(mx, 32));
;                 const float mnew = fmaxf(mrun[qt], mx); const float alpha = __builtin_amdgcn_exp2f(mrun[qt] - mnew); mrun[qt] = mnew;
;                 float ps = 0.f;
; #pragma unroll
;                 for (int nt = 0; nt < 2; ++nt)
; #pragma unroll
;                     for (int j = 0; j < 4; ++j) { const float p = __builtin_amdgcn_exp2f(s[nt][j] - mnew); s[nt][j] = p; ps += p; }
;                 lrun[qt] = lrun[qt] * alpha + ps;
; #pragma unroll
;                 for (int dt = 0; dt < 4; ++dt) o[qt][dt] = o[qt][dt] * alpha;
;             } else {
;                 float lk[2][4], c4[2];
; #pragma unroll
;                 for (int nt = 0; nt < 2; ++nt) { c4[nt] = 0.f;
; #pragma unroll
;                     for (int j = 0; j < 4; ++j) { const bool valid = (dbase - (16 * nt + j)) > 0; const float z = s[nt][j] * C1;
;                         const float e = __builtin_amdgcn_exp2f(-fabsf(z));
;                         const float sp = fmaxf(z, 0.f) + __builtin_amdgcn_logf(1.f + e);
.LBB0_344:
	s_mov_b32 s10, 0xc316199a
	s_cmp_gt_u32 s47, s46
	v_cmp_gt_f32_e32 vcc, s10, v107
	s_cselect_b64 s[0:1], -1, 0
	s_cmp_eq_u64 vcc, exec
	s_cselect_b64 s[10:11], -1, 0
	s_or_b64 s[0:1], s[0:1], s[10:11]
	s_and_b64 vcc, exec, s[0:1]
	s_cbranch_vccnz .LBB0_337
	v_mfma_f32_16x16x32_bf16 v[132:135], v[132:135], v[64:67], 0
	s_mov_b32 s15, 0x3e38aa3b
	v_cmp_gt_u32_e32 vcc, v150, v163
	v_cmp_gt_u32_e64 s[10:11], v141, v158
	v_mfma_f32_16x16x32_bf16 v[132:135], v[136:139], v[72:75], v[132:135]
	v_cmp_gt_u32_e64 s[0:1], v150, v159
	v_mfma_f32_16x16x32_bf16 v[128:131], v[128:131], v[64:67], 0
	v_mfma_f32_16x16x32_bf16 v[124:127], v[124:127], v[72:75], v[128:131]
	s_nop 2
	v_mul_f32_e32 v136, 0x3e38aa3b, v133
	v_exp_f32_e64 v138, -|v136|
	v_mul_f32_e32 v1, 0x3e38aa3b, v132
	v_exp_f32_e64 v137, -|v1|
	v_max_f32_e32 v129, 0, v136
	v_add_f32_e32 v138, 1.0, v138
	v_log_f32_e32 v128, v138
	v_add_f32_e32 v137, 1.0, v137
	v_log_f32_e32 v137, v137
	v_max_f32_e32 v1, 0, v1
	v_add_f32_e32 v129, v129, v128
	v_cndmask_b32_e64 v128, 0, -v129, vcc
	v_fma_f32 v129, v133, s15, -v129
	v_cndmask_b32_e32 v163, v226, v129, vcc
	v_mul_f32_e32 v129, 0x3e38aa3b, v134
	v_exp_f32_e64 v131, -|v129|
	v_mul_f32_e32 v133, 0x3e38aa3b, v135
	v_exp_f32_e64 v136, -|v133|
	v_add_f32_e32 v1, v1, v137
	v_max_f32_e32 v130, 0, v129
	v_add_f32_e32 v129, 1.0, v131
	v_fma_f32 v137, v132, s15, -v1
	v_log_f32_e32 v132, v129
	v_add_f32_e32 v129, 1.0, v136
	v_max_f32_e32 v131, 0, v133
	v_mul_f32_e32 v133, 0x3e38aa3b, v124
	v_log_f32_e32 v129, v129
	v_exp_f32_e64 v138, -|v133|
	v_cmp_gt_u32_e32 vcc, v150, v162
	v_sub_f32_e32 v1, 0, v1
	v_add_f32_e32 v129, v131, v129
	v_add_f32_e32 v131, 1.0, v138
	v_log_f32_e32 v131, v131
	v_cndmask_b32_e64 v136, 0, -v129, vcc
	v_fma_f32 v129, v135, s15, -v129
	v_cndmask_b32_e32 v162, v226, v129, vcc
	v_max_f32_e32 v129, 0, v133
	v_add_f32_e32 v129, v129, v131
	v_mul_f32_e32 v131, 0x3e38aa3b, v125
	v_exp_f32_e64 v133, -|v131|
	v_fma_f32 v124, v124, s15, -v129
	v_cmp_gt_u32_e32 vcc, v150, v161
	v_max_f32_e32 v131, 0, v131
	v_sub_f32_e32 v129, 0, v129
	v_cndmask_b32_e32 v138, v226, v124, vcc
	v_add_f32_e32 v124, 1.0, v133
	v_log_f32_e32 v124, v124
	v_cndmask_b32_e32 v129, 0, v129, vcc
	v_cmp_gt_u32_e32 vcc, v150, v160
	v_add_f32_e32 v124, v131, v124
	v_mul_f32_e32 v131, 0x3e38aa3b, v126
	v_exp_f32_e64 v133, -|v131|
	v_cndmask_b32_e64 v139, 0, -v124, vcc
	v_fma_f32 v124, v125, s15, -v124
	v_cndmask_b32_e32 v160, v226, v124, vcc
	v_add_f32_e32 v124, 1.0, v133
	v_max_f32_e32 v125, 0, v131
	v_mul_f32_e32 v131, 0x3e38aa3b, v127
	v_log_f32_e32 v124, v124
	v_exp_f32_e64 v133, -|v131|
	v_cmp_lt_i32_e32 vcc, v223, v218
	v_max_f32_e32 v131, 0, v131
	v_add_f32_e32 v135, v125, v124
	v_add_f32_e32 v124, 1.0, v133
	v_log_f32_e32 v133, v124
	v_cndmask_b32_e32 v124, v217, v223, vcc
	v_cmp_lt_i32_e32 vcc, v224, v218
	v_lshlrev_b32_e32 v161, 2, v124
	v_add_f32_e32 v129, v139, v129
	v_cndmask_b32_e32 v124, v217, v224, vcc
	v_lshlrev_b32_e32 v164, 2, v124
	v_xor_b32_e32 v124, 48, v217
	v_cmp_lt_i32_e32 vcc, v124, v218
	v_fma_f32 v126, v126, s15, -v135
	v_cndmask_b32_e64 v158, v226, v126, s[10:11]
	v_cndmask_b32_e32 v124, v217, v124, vcc
	v_lshlrev_b32_e32 v165, 2, v124
	v_cmp_gt_u32_e32 vcc, v150, v3
	v_pk_add_f32 v[124:125], v[130:131], v[132:133]
	v_cndmask_b32_e64 v131, 0, -v135, s[10:11]
	v_cndmask_b32_e32 v166, v226, v137, vcc
	v_fma_f32 v3, v134, s15, -v124
	v_cndmask_b32_e32 v130, 0, v1, vcc
	v_cmp_gt_u32_e32 vcc, v141, v2
	v_cndmask_b32_e64 v159, v226, v3, s[0:1]
	v_pk_add_f32 v[132:133], v[130:131], v[128:129]
	v_cndmask_b32_e64 v3, 0, -v125, vcc
	v_cndmask_b32_e64 v2, 0, -v124, s[0:1]
	v_pk_add_f32 v[132:133], v[2:3], v[132:133]
	ds_bpermute_b32 v137, v161, v133
	v_fma_f32 v1, v127, s15, -v125
	ds_bpermute_b32 v125, v164, v133
	ds_bpermute_b32 v127, v165, v133
	v_cndmask_b32_e32 v129, v226, v1, vcc
	s_waitcnt lgkmcnt(2)
	v_cndmask_b32_e64 v1, 0, v137, s[4:5]
	v_mov_b32_e32 v134, v107
	s_waitcnt lgkmcnt(1)
	v_cndmask_b32_e64 v126, 0, v125, s[6:7]
	v_add_f32_e32 v135, v1, v126
	s_waitcnt lgkmcnt(0)
	v_cndmask_b32_e64 v1, 0, v127, s[8:9]
	v_pk_add_f32 v[134:135], v[134:135], v[0:1]
	v_pk_add_f32 v[132:133], v[136:137], v[132:133]
	v_add_f32_e32 v1, v134, v135
	v_add_f32_e32 v129, v1, v129
	v_add_f32_e32 v1, v1, v3
	ds_bpermute_b32 v124, v161, v132
	ds_bpermute_b32 v126, v164, v132
	v_add_f32_e32 v3, v1, v158
	v_add_f32_e32 v1, v131, v1
	v_add_f32_e32 v130, v160, v1
	v_exp_f32_e32 v137, v130
	ds_bpermute_b32 v130, v165, v132
	s_waitcnt lgkmcnt(2)
	v_cndmask_b32_e64 v131, 0, v124, s[4:5]
	s_waitcnt lgkmcnt(1)
	v_cndmask_b32_e64 v134, 0, v126, s[6:7]
	v_pk_add_f32 v[124:125], v[132:133], v[124:125]
	v_add_f32_e32 v1, v139, v1
	v_add_f32_e32 v134, v131, v134
	v_pk_add_f32 v[124:125], v[124:125], v[126:127]
	v_mov_b32_e32 v131, v0
	v_add_f32_e32 v1, v138, v1
	s_waitcnt lgkmcnt(0)
	v_cndmask_b32_e64 v138, 0, v130, s[8:9]
	v_pk_add_f32 v[130:131], v[124:125], v[130:131]
	v_mov_b32_e32 v135, v107
	v_mov_b32_e32 v139, v131
	v_pk_add_f32 v[124:125], v[134:135], v[138:139]
	v_exp_f32_e32 v129, v129
	v_add_f32_e32 v124, v124, v125
	v_add_f32_e32 v125, v162, v124
	v_add_f32_e32 v124, v136, v124
	v_add_f32_e32 v2, v2, v124
	v_add_f32_e32 v126, v159, v124
	v_add_f32_e32 v124, v163, v2
	v_add_f32_e32 v2, v128, v2
	v_add_f32_e32 v2, v166, v2
	v_exp_f32_e32 v125, v125
	v_exp_f32_e32 v124, v124
	v_exp_f32_e32 v2, v2
	v_exp_f32_e32 v126, v126
	v_exp_f32_e32 v1, v1
	v_exp_f32_e32 v3, v3
	v_cvt_pk_bf16_f32 v124, v2, v124
	v_cvt_pk_bf16_f32 v125, v126, v125
	v_cvt_pk_bf16_f32 v126, v1, v137
	v_cvt_pk_bf16_f32 v127, v3, v129
	v_add_f32_e32 v1, v130, v131
	v_add_f32_e32 v107, v107, v1
	v_mfma_f32_16x16x32_bf16 v[20:23], v[112:115], v[124:127], v[20:23]
	v_mfma_f32_16x16x32_bf16 v[16:19], v[108:111], v[124:127], v[16:19]
	v_mfma_f32_16x16x32_bf16 v[12:15], v[116:119], v[124:127], v[12:15]
	v_mfma_f32_16x16x32_bf16 v[8:11], v[120:123], v[124:127], v[8:11]
	s_branch .LBB0_337
